# attention: context image DMA pieces spread over the MFMAs of the context-QK / context-PV blocks (MFMA shadow) instead of one burst in front of them; on top of v43
# baseline (speedup 1.0000x reference)
; #define LAS __attribute__((address_space(3)))
; template <bool LOCAL>
; __device__ __forceinline__ void attn_unit(const bf16_t* Q, const bf16_t* KT, const bf16_t* VT, bf16_t* O, LAS unsigned char* lds, int b, int h, int r, int w, int tq, int lane) {
;     ...
;     {
;         const LAS unsigned char* vl = lds + 65536 + g * 2048 + q * 16;
; #pragma unroll
;         for (int p = 0; p < 8; ++p)
; #pragma unroll
;             for (int df = 0; df < 8; ++df) o[df] = __builtin_amdgcn_mfma_f32_16x16x32_bf16(*(const LAS bf16x8*)(vl + p * 8192 + df * 256), pb[CP + p], o[df], 0, 0, 0);
;     }
; __global__ void __launch_bounds__(NTHREADS, 2) mega(Args args) {
;     ...
;                     { const int oc0 = (ML + b * CTX) >> 3;
;                       for (int ci = tid; ci < 4096; ci += NTHREADS) { const int o = ci >> 7, wq = ci & 127;
;                           const u32x4 kv = *(const u32x4*)(KTp + ((size_t)((oc0 + o) * NH + h)) * 1024 + wq * 8);
;                           *(LAS u32x4*)(lds + o * 2048 + (wq & ~15) * 16 + ((wq & 15) ^ (o & 2)) * 16) = kv;
;                           const u32x4 vv = *(const u32x4*)(VTp + ((size_t)((oc0 + o) * NH + h)) * 1024 + wq * 8);
;                           *(LAS u32x4*)(lds + 65536 + o * 2048 + wq * 16) = vv; }
.Lrg_v_B_end:
.Lrg_v_done:
	s_barrier
	s_waitcnt lgkmcnt(0)
	s_add_i32 s48, s48, 2
	s_add_i32 s52, s52, s80
	s_sub_i32 s51, s51, s80
	s_lshl_b32 s82, s80, 6
	v_add_u32_e32 v162, s82, v162
	ds_read_b128 v[200:203], v178
	ds_read_b128 v[204:207], v178 offset:256
	ds_read_b128 v[208:211], v178 offset:512
	ds_read_b128 v[212:215], v178 offset:768
	ds_read_b128 v[216:219], v178 offset:1024
	ds_read_b128 v[220:223], v178 offset:1280
	ds_read_b128 v[224:227], v178 offset:1536
	ds_read_b128 v[228:231], v178 offset:1792
	s_waitcnt lgkmcnt(7)
	v_mfma_f32_16x16x32_bf16 v[22:25], v[200:203], v[98:101], v[22:25]
	v_mov_b32_e32 v248, v234
	v_mov_b32_e32 v249, v235
	s_lshl_b32 s55, s57, 10
	s_add_i32 m0, s55, 0
	s_nop 0
	global_load_lds_dwordx4 v[248:249], off
	ds_read_b128 v[200:203], v178 offset:8192
	s_waitcnt lgkmcnt(7)
	v_mfma_f32_16x16x32_bf16 v[30:33], v[204:207], v[98:101], v[30:33]
	ds_read_b128 v[204:207], v178 offset:8448
	s_waitcnt lgkmcnt(7)
	v_mfma_f32_16x16x32_bf16 v[34:37], v[208:211], v[98:101], v[34:37]
	ds_read_b128 v[208:211], v178 offset:8704
	s_waitcnt lgkmcnt(7)
	v_mfma_f32_16x16x32_bf16 v[38:41], v[212:215], v[98:101], v[38:41]
	ds_read_b128 v[212:215], v178 offset:8960
	s_waitcnt lgkmcnt(7)
	v_mfma_f32_16x16x32_bf16 v[42:45], v[216:219], v[98:101], v[42:45]
	ds_read_b128 v[216:219], v178 offset:9216
	s_waitcnt lgkmcnt(7)
	v_mfma_f32_16x16x32_bf16 v[46:49], v[220:223], v[98:101], v[46:49]
	ds_read_b128 v[220:223], v178 offset:9472
	s_waitcnt lgkmcnt(7)
	v_mfma_f32_16x16x32_bf16 v[50:53], v[224:227], v[98:101], v[50:53]
	ds_read_b128 v[224:227], v178 offset:9728
	s_waitcnt lgkmcnt(7)
	v_mfma_f32_16x16x32_bf16 v[54:57], v[228:231], v[98:101], v[54:57]
	ds_read_b128 v[228:231], v178 offset:9984
	s_waitcnt lgkmcnt(7)
	v_mfma_f32_16x16x32_bf16 v[22:25], v[200:203], v[90:93], v[22:25]
	v_add_co_u32_e32 v248, vcc, 0x20000, v248
	s_nop 1
	v_addc_co_u32_e32 v249, vcc, 0, v249, vcc
	s_add_i32 m0, s55, 8192
	s_nop 0
	global_load_lds_dwordx4 v[248:249], off
	ds_read_b128 v[200:203], v178 offset:16384
	s_waitcnt lgkmcnt(7)
	v_mfma_f32_16x16x32_bf16 v[30:33], v[204:207], v[90:93], v[30:33]
	ds_read_b128 v[204:207], v178 offset:16640
	s_waitcnt lgkmcnt(7)
	v_mfma_f32_16x16x32_bf16 v[34:37], v[208:211], v[90:93], v[34:37]
	ds_read_b128 v[208:211], v178 offset:16896
	s_waitcnt lgkmcnt(7)
	v_mfma_f32_16x16x32_bf16 v[38:41], v[212:215], v[90:93], v[38:41]
	ds_read_b128 v[212:215], v178 offset:17152
	s_waitcnt lgkmcnt(7)
	v_mfma_f32_16x16x32_bf16 v[42:45], v[216:219], v[90:93], v[42:45]
	ds_read_b128 v[216:219], v178 offset:17408
	s_waitcnt lgkmcnt(7)
	v_mfma_f32_16x16x32_bf16 v[46:49], v[220:223], v[90:93], v[46:49]
	ds_read_b128 v[220:223], v178 offset:17664
	s_waitcnt lgkmcnt(7)
	v_mfma_f32_16x16x32_bf16 v[50:53], v[224:227], v[90:93], v[50:53]
	ds_read_b128 v[224:227], v178 offset:17920
	s_waitcnt lgkmcnt(7)
	v_mfma_f32_16x16x32_bf16 v[54:57], v[228:231], v[90:93], v[54:57]
	ds_read_b128 v[228:231], v178 offset:18176
	s_waitcnt lgkmcnt(7)
	v_mfma_f32_16x16x32_bf16 v[22:25], v[200:203], v[26:29], v[22:25]
	v_add_co_u32_e32 v248, vcc, 0x20000, v248
	s_nop 1
	v_addc_co_u32_e32 v249, vcc, 0, v249, vcc
	s_add_i32 m0, s55, 16384
	s_nop 0
	global_load_lds_dwordx4 v[248:249], off
	ds_read_b128 v[200:203], v178 offset:24576
	s_waitcnt lgkmcnt(7)
	v_mfma_f32_16x16x32_bf16 v[30:33], v[204:207], v[26:29], v[30:33]
	ds_read_b128 v[204:207], v178 offset:24832
	s_waitcnt lgkmcnt(7)
	v_mfma_f32_16x16x32_bf16 v[34:37], v[208:211], v[26:29], v[34:37]
	ds_read_b128 v[208:211], v178 offset:25088
	s_waitcnt lgkmcnt(7)
	v_mfma_f32_16x16x32_bf16 v[38:41], v[212:215], v[26:29], v[38:41]
	ds_read_b128 v[212:215], v178 offset:25344
	s_waitcnt lgkmcnt(7)
	v_mfma_f32_16x16x32_bf16 v[42:45], v[216:219], v[26:29], v[42:45]
	ds_read_b128 v[216:219], v178 offset:25600
	s_waitcnt lgkmcnt(7)
	v_mfma_f32_16x16x32_bf16 v[46:49], v[220:223], v[26:29], v[46:49]
	ds_read_b128 v[220:223], v178 offset:25856
	s_waitcnt lgkmcnt(7)
	v_mfma_f32_16x16x32_bf16 v[50:53], v[224:227], v[26:29], v[50:53]
	ds_read_b128 v[224:227], v178 offset:26112
	s_waitcnt lgkmcnt(7)
	v_mfma_f32_16x16x32_bf16 v[26:29], v[228:231], v[26:29], v[54:57]
	ds_read_b128 v[228:231], v178 offset:26368
	s_waitcnt lgkmcnt(7)
	v_mfma_f32_16x16x32_bf16 v[22:25], v[200:203], v[10:13], v[22:25]
	v_add_co_u32_e32 v248, vcc, 0x20000, v248
	s_nop 1
	v_addc_co_u32_e32 v249, vcc, 0, v249, vcc
	s_add_i32 m0, s55, 24576
	s_nop 0
	global_load_lds_dwordx4 v[248:249], off
	ds_read_b128 v[200:203], v178 offset:32768
	s_waitcnt lgkmcnt(7)
	v_mfma_f32_16x16x32_bf16 v[30:33], v[204:207], v[10:13], v[30:33]
	ds_read_b128 v[204:207], v178 offset:33024
	s_waitcnt lgkmcnt(7)
	v_mfma_f32_16x16x32_bf16 v[34:37], v[208:211], v[10:13], v[34:37]
	ds_read_b128 v[208:211], v178 offset:33280
	s_waitcnt lgkmcnt(7)
	v_mfma_f32_16x16x32_bf16 v[38:41], v[212:215], v[10:13], v[38:41]
	ds_read_b128 v[212:215], v178 offset:33536
	s_waitcnt lgkmcnt(7)
	v_mfma_f32_16x16x32_bf16 v[42:45], v[216:219], v[10:13], v[42:45]
	ds_read_b128 v[216:219], v178 offset:33792
	s_waitcnt lgkmcnt(7)
	v_mfma_f32_16x16x32_bf16 v[46:49], v[220:223], v[10:13], v[46:49]
	ds_read_b128 v[220:223], v178 offset:34048
	s_waitcnt lgkmcnt(7)
	v_mfma_f32_16x16x32_bf16 v[50:53], v[224:227], v[10:13], v[50:53]
	ds_read_b128 v[224:227], v178 offset:34304
	s_waitcnt lgkmcnt(7)
	v_mfma_f32_16x16x32_bf16 v[10:13], v[228:231], v[10:13], v[26:29]
	ds_read_b128 v[228:231], v178 offset:34560
	s_waitcnt lgkmcnt(7)
	v_mfma_f32_16x16x32_bf16 v[22:25], v[200:203], v[2:5], v[22:25]
	v_add_co_u32_e32 v248, vcc, 0x20000, v248
	s_nop 1
	v_addc_co_u32_e32 v249, vcc, 0, v249, vcc
	s_add_i32 m0, s55, 32768
	s_nop 0
	global_load_lds_dwordx4 v[248:249], off
	ds_read_b128 v[200:203], v178 offset:40960
	s_waitcnt lgkmcnt(7)
; #define LAS __attribute__((address_space(3)))
; __device__ __forceinline__ unsigned cvt_pk_bf16(float lo, float hi) { unsigned r; asm volatile("v_cvt_pk_bf16_f32 %0, %1, %2" : "=v"(r) : "v"(lo), "v"(hi)); return r; }
; template <bool LOCAL>
; __device__ __forceinline__ void attn_unit(const bf16_t* Q, const bf16_t* KT, const bf16_t* VT, bf16_t* O, LAS unsigned char* lds, int b, int h, int r, int w, int tq, int lane) {
;     ...
;     {
;         const LAS unsigned char* vl = lds + 65536 + g * 2048 + q * 16;
; #pragma unroll
;         for (int p = 0; p < 8; ++p)
; #pragma unroll
;             for (int df = 0; df < 8; ++df) o[df] = __builtin_amdgcn_mfma_f32_16x16x32_bf16(*(const LAS bf16x8*)(vl + p * 8192 + df * 256), pb[CP + p], o[df], 0, 0, 0);
;     }
;     const float inv = 1.f / sum;
;     bf16_t* op = O + (size_t)qrow * D + h * HD + 4 * g;
; #pragma unroll
;     for (int df = 0; df < 8; ++df) { u32x2 wv; wv.x = cvt_pk_bf16(o[df][0] * inv, o[df][1] * inv); wv.y = cvt_pk_bf16(o[df][2] * inv, o[df][3] * inv); *(u32x2*)(op + 16 * df) = wv; }
; __global__ void __launch_bounds__(NTHREADS, 2) mega(Args args) {
;     ...
;                     { const int oc0 = (ML + b * CTX) >> 3;
;                       for (int ci = tid; ci < 4096; ci += NTHREADS) { const int o = ci >> 7, wq = ci & 127;
;                           const u32x4 kv = *(const u32x4*)(KTp + ((size_t)((oc0 + o) * NH + h)) * 1024 + wq * 8);
;                           *(LAS u32x4*)(lds + o * 2048 + (wq & ~15) * 16 + ((wq & 15) ^ (o & 2)) * 16) = kv;
;                           const u32x4 vv = *(const u32x4*)(VTp + ((size_t)((oc0 + o) * NH + h)) * 1024 + wq * 8);
;                           *(LAS u32x4*)(lds + 65536 + o * 2048 + wq * 16) = vv; }
	v_mfma_f32_16x16x32_bf16 v[26:29], v[204:207], v[2:5], v[30:33]
	ds_read_b128 v[204:207], v178 offset:41216
	s_waitcnt lgkmcnt(7)
	v_mfma_f32_16x16x32_bf16 v[30:33], v[208:211], v[2:5], v[34:37]
	ds_read_b128 v[208:211], v178 offset:41472
	s_waitcnt lgkmcnt(7)
	v_mfma_f32_16x16x32_bf16 v[34:37], v[212:215], v[2:5], v[38:41]
	ds_read_b128 v[212:215], v178 offset:41728
	s_waitcnt lgkmcnt(7)
	v_mfma_f32_16x16x32_bf16 v[38:41], v[216:219], v[2:5], v[42:45]
	ds_read_b128 v[216:219], v178 offset:41984
	s_waitcnt lgkmcnt(7)
	v_mfma_f32_16x16x32_bf16 v[42:45], v[220:223], v[2:5], v[46:49]
	ds_read_b128 v[220:223], v178 offset:42240
	s_waitcnt lgkmcnt(7)
	v_mfma_f32_16x16x32_bf16 v[46:49], v[224:227], v[2:5], v[50:53]
	ds_read_b128 v[224:227], v178 offset:42496
	s_waitcnt lgkmcnt(7)
	v_mfma_f32_16x16x32_bf16 v[2:5], v[228:231], v[2:5], v[10:13]
	ds_read_b128 v[228:231], v178 offset:42752
	s_waitcnt lgkmcnt(7)
	v_mfma_f32_16x16x32_bf16 v[10:13], v[200:203], v[6:9], v[22:25]
	v_add_co_u32_e32 v248, vcc, 0x20000, v248
	s_nop 1
	v_addc_co_u32_e32 v249, vcc, 0, v249, vcc
	s_add_i32 m0, s55, 40960
	s_nop 0
	global_load_lds_dwordx4 v[248:249], off
	ds_read_b128 v[200:203], v178 offset:49152
	s_waitcnt lgkmcnt(7)
	v_mfma_f32_16x16x32_bf16 v[22:25], v[204:207], v[6:9], v[26:29]
	ds_read_b128 v[204:207], v178 offset:49408
	s_waitcnt lgkmcnt(7)
	v_mfma_f32_16x16x32_bf16 v[26:29], v[208:211], v[6:9], v[30:33]
	ds_read_b128 v[208:211], v178 offset:49664
	s_waitcnt lgkmcnt(7)
	v_mfma_f32_16x16x32_bf16 v[30:33], v[212:215], v[6:9], v[34:37]
	ds_read_b128 v[212:215], v178 offset:49920
	s_waitcnt lgkmcnt(7)
	v_mfma_f32_16x16x32_bf16 v[34:37], v[216:219], v[6:9], v[38:41]
	ds_read_b128 v[216:219], v178 offset:50176
	s_waitcnt lgkmcnt(7)
	v_mfma_f32_16x16x32_bf16 v[38:41], v[220:223], v[6:9], v[42:45]
	ds_read_b128 v[220:223], v178 offset:50432
	s_waitcnt lgkmcnt(7)
	v_mfma_f32_16x16x32_bf16 v[42:45], v[224:227], v[6:9], v[46:49]
	ds_read_b128 v[224:227], v178 offset:50688
	s_waitcnt lgkmcnt(7)
	v_mfma_f32_16x16x32_bf16 v[2:5], v[228:231], v[6:9], v[2:5]
	ds_read_b128 v[228:231], v178 offset:50944
	s_waitcnt lgkmcnt(7)
	v_mfma_f32_16x16x32_bf16 v[6:9], v[200:203], v[14:17], v[10:13]
	v_add_co_u32_e32 v248, vcc, 0x20000, v248
	s_nop 1
	v_addc_co_u32_e32 v249, vcc, 0, v249, vcc
	s_add_i32 m0, s55, 49152
	s_nop 0
	global_load_lds_dwordx4 v[248:249], off
	ds_read_b128 v[200:203], v178 offset:57344
	s_waitcnt lgkmcnt(7)
	v_mfma_f32_16x16x32_bf16 v[10:13], v[204:207], v[14:17], v[22:25]
	ds_read_b128 v[204:207], v178 offset:57600
	s_waitcnt lgkmcnt(7)
	v_mfma_f32_16x16x32_bf16 v[22:25], v[208:211], v[14:17], v[26:29]
	ds_read_b128 v[208:211], v178 offset:57856
	s_waitcnt lgkmcnt(7)
	v_mfma_f32_16x16x32_bf16 v[26:29], v[212:215], v[14:17], v[30:33]
	ds_read_b128 v[212:215], v178 offset:58112
	s_waitcnt lgkmcnt(7)
	v_mfma_f32_16x16x32_bf16 v[30:33], v[216:219], v[14:17], v[34:37]
	ds_read_b128 v[216:219], v178 offset:58368
	s_waitcnt lgkmcnt(7)
	v_mfma_f32_16x16x32_bf16 v[34:37], v[220:223], v[14:17], v[38:41]
	ds_read_b128 v[220:223], v178 offset:58624
	s_waitcnt lgkmcnt(7)
	v_mfma_f32_16x16x32_bf16 v[38:41], v[224:227], v[14:17], v[42:45]
	ds_read_b128 v[224:227], v178 offset:58880
	s_waitcnt lgkmcnt(7)
	v_mfma_f32_16x16x32_bf16 v[2:5], v[228:231], v[14:17], v[2:5]
	ds_read_b128 v[228:231], v178 offset:59136
	s_waitcnt lgkmcnt(7)
	v_mfma_f32_16x16x32_bf16 v[6:9], v[200:203], v[18:21], v[6:9]
	v_add_co_u32_e32 v248, vcc, 0x20000, v248
	s_nop 1
	v_addc_co_u32_e32 v249, vcc, 0, v249, vcc
	s_add_i32 m0, s55, 57344
	s_nop 0
	global_load_lds_dwordx4 v[248:249], off
	s_waitcnt lgkmcnt(6)
	v_mfma_f32_16x16x32_bf16 v[10:13], v[204:207], v[18:21], v[10:13]
	s_waitcnt lgkmcnt(5)
	v_mfma_f32_16x16x32_bf16 v[14:17], v[208:211], v[18:21], v[22:25]
	s_waitcnt lgkmcnt(4)
	v_mfma_f32_16x16x32_bf16 v[22:25], v[212:215], v[18:21], v[26:29]
	s_waitcnt lgkmcnt(3)
	v_mfma_f32_16x16x32_bf16 v[26:29], v[216:219], v[18:21], v[30:33]
	s_waitcnt lgkmcnt(2)
	v_mfma_f32_16x16x32_bf16 v[30:33], v[220:223], v[18:21], v[34:37]
	s_waitcnt lgkmcnt(1)
	v_mfma_f32_16x16x32_bf16 v[34:37], v[224:227], v[18:21], v[38:41]
	s_waitcnt lgkmcnt(0)
	v_mfma_f32_16x16x32_bf16 v[2:5], v[228:231], v[18:21], v[2:5]
	s_nop 7
	s_cmp_eq_u32 s48, 8
	v_add_f32_e32 v18, v134, v135
	v_div_scale_f32 v19, s[4:5], v18, v18, 1.0
	v_rcp_f32_e32 v20, v19
	s_nop 0
	v_fma_f32 v21, -v19, v20, 1.0
	v_fmac_f32_e32 v20, v21, v20
	v_div_scale_f32 v21, vcc, 1.0, v18, 1.0
	v_mul_f32_e32 v38, v21, v20
	v_fma_f32 v39, -v19, v38, v21
	v_fmac_f32_e32 v38, v39, v20
	v_fma_f32 v19, -v19, v38, v21
	v_div_fmas_f32 v19, v19, v20, v38
	v_div_fixup_f32 v20, v19, v18, 1.0
	v_mul_f32_e32 v6, v20, v6
	v_mul_f32_e32 v7, v20, v7
	v_cvt_pk_bf16_f32 v6, v6, v7
	v_mul_f32_e32 v7, v20, v8
	v_lshl_add_u64 v[18:19], v[130:131], 1, v[160:161]
	v_mul_f32_e32 v8, v20, v9
	v_cvt_pk_bf16_f32 v7, v7, v8
	global_store_dwordx2 v[18:19], v[6:7], off
	v_mul_f32_e32 v6, v20, v10
	v_mul_f32_e32 v7, v20, v11
	v_cvt_pk_bf16_f32 v6, v6, v7
	v_mul_f32_e32 v7, v20, v12
	v_mul_f32_e32 v8, v20, v13
	v_cvt_pk_bf16_f32 v7, v7, v8
	global_store_dwordx2 v[18:19], v[6:7], off offset:32
	v_mul_f32_e32 v6, v20, v14
	v_mul_f32_e32 v7, v20, v15
	v_cvt_pk_bf16_f32 v6, v6, v7
	v_mul_f32_e32 v7, v20, v16
	v_mul_f32_e32 v8, v20, v17
	v_cvt_pk_bf16_f32 v7, v7, v8
	global_store_dwordx2 v[18:19], v[6:7], off offset:64
	v_mul_f32_e32 v6, v20, v22
	v_mul_f32_e32 v7, v20, v23
	v_cvt_pk_bf16_f32 v6, v6, v7
	v_mul_f32_e32 v7, v20, v24
	v_mul_f32_e32 v8, v20, v25
	v_cvt_pk_bf16_f32 v7, v7, v8
	global_store_dwordx2 v[18:19], v[6:7], off offset:96
	v_mul_f32_e32 v6, v20, v26
	v_mul_f32_e32 v7, v20, v27
	v_cvt_pk_bf16_f32 v6, v6, v7
	v_mul_f32_e32 v7, v20, v28
	v_mul_f32_e32 v8, v20, v29
	v_cvt_pk_bf16_f32 v7, v7, v8
	global_store_dwordx2 v[18:19], v[6:7], off offset:128
	v_mul_f32_e32 v6, v20, v30
	v_mul_f32_e32 v7, v20, v31
	v_cvt_pk_bf16_f32 v6, v6, v7
	v_mul_f32_e32 v7, v20, v32
	v_mul_f32_e32 v8, v20, v33
	v_cvt_pk_bf16_f32 v7, v7, v8
	global_store_dwordx2 v[18:19], v[6:7], off offset:160
	v_mul_f32_e32 v6, v20, v34
	v_mul_f32_e32 v7, v20, v35
	v_cvt_pk_bf16_f32 v6, v6, v7
	v_mul_f32_e32 v7, v20, v36
	v_mul_f32_e32 v2, v20, v2
	v_mul_f32_e32 v3, v20, v3
	v_mul_f32_e32 v8, v20, v37
	v_cvt_pk_bf16_f32 v7, v7, v8
	global_store_dwordx2 v[18:19], v[6:7], off offset:192
	v_cvt_pk_bf16_f32 v2, v2, v3
	v_mul_f32_e32 v3, v20, v4
	v_mul_f32_e32 v4, v20, v5
	v_cvt_pk_bf16_f32 v3, v3, v4
	global_store_dwordx2 v[18:19], v[2:3], off offset:224
	s_waitcnt vmcnt(0)
	s_barrier
	s_cbranch_scc1 .LBB9_802

; #define LAS __attribute__((address_space(3)))
; template <bool LOCAL>
; __device__ __forceinline__ void attn_unit(const bf16_t* Q, const bf16_t* KT, const bf16_t* VT, bf16_t* O, LAS unsigned char* lds, int b, int h, int r, int w, int tq, int lane) {
;     ...
;     {
;         const LAS unsigned char* kl = lds + (q >> 2) * 2048 + (((q & 3) * 4 + g) ^ ((q >> 2) & 2)) * 16;
; #pragma unroll
;         for (int p = 0; p < 8; ++p)
; #pragma unroll
;             for (int f = 0; f < 2; ++f) { f32x4 a = {0.f, 0.f, 0.f, 0.f};
; #pragma unroll
;                 for (int ks = 0; ks < 4; ++ks) a = __builtin_amdgcn_mfma_f32_16x16x32_bf16(*(const LAS bf16x8*)(kl + p * 8192 + ks * 512 + f * 256), bq[ks], a, 0, 0, 0);
;                 s[2 * (CP + p) + f] = a; }
;     }
; __global__ void __launch_bounds__(NTHREADS, 2) mega(Args args) {
;     ...
;                     { const int oc0 = (ML + b * CTX) >> 3;
;                       for (int ci = tid; ci < 4096; ci += NTHREADS) { const int o = ci >> 7, wq = ci & 127;
;                           const u32x4 kv = *(const u32x4*)(KTp + ((size_t)((oc0 + o) * NH + h)) * 1024 + wq * 8);
;                           *(LAS u32x4*)(lds + o * 2048 + (wq & ~15) * 16 + ((wq & 15) ^ (o & 2)) * 16) = kv;
;                           const u32x4 vv = *(const u32x4*)(VTp + ((size_t)((oc0 + o) * NH + h)) * 1024 + wq * 8);
;                           *(LAS u32x4*)(lds + 65536 + o * 2048 + wq * 16) = vv; }
.Lrg_k_B_end:
.Lrg_k_done:
	s_barrier
	s_nop 5
	s_waitcnt lgkmcnt(0)
	s_movk_i32 s4, 0x7c
	ds_read_b128 v[200:203], v169
	ds_read_b128 v[204:207], v169 offset:512
	ds_read_b128 v[208:211], v169 offset:1024
	ds_read_b128 v[212:215], v169 offset:1536
	ds_read_b128 v[216:219], v169 offset:256
	ds_read_b128 v[220:223], v169 offset:768
	ds_read_b128 v[224:227], v169 offset:1280
	ds_read_b128 v[228:231], v169 offset:1792
	s_waitcnt lgkmcnt(7)
	v_mfma_f32_16x16x32_bf16 v[2:5], v[200:203], v[138:141], 0
	v_mov_b32_e32 v248, v236
	v_mov_b32_e32 v249, v237
	s_lshl_b32 s55, s57, 10
	s_add_i32 m0, s55, 65536
	s_nop 0
	global_load_lds_dwordx4 v[248:249], off
	ds_read_b128 v[200:203], v169 offset:8192
	s_waitcnt lgkmcnt(7)
	v_mfma_f32_16x16x32_bf16 v[2:5], v[204:207], v[134:137], v[2:5]
	ds_read_b128 v[204:207], v169 offset:8704
	s_waitcnt lgkmcnt(7)
	v_mfma_f32_16x16x32_bf16 v[2:5], v[208:211], v[130:133], v[2:5]
	ds_read_b128 v[208:211], v169 offset:9216
	s_waitcnt lgkmcnt(7)
	v_mfma_f32_16x16x32_bf16 v[2:5], v[212:215], v[62:65], v[2:5]
	ds_read_b128 v[212:215], v169 offset:9728
	s_waitcnt lgkmcnt(7)
	v_mfma_f32_16x16x32_bf16 v[6:9], v[216:219], v[138:141], 0
	ds_read_b128 v[216:219], v169 offset:8448
	s_waitcnt lgkmcnt(7)
	v_mfma_f32_16x16x32_bf16 v[6:9], v[220:223], v[134:137], v[6:9]
	ds_read_b128 v[220:223], v169 offset:8960
	s_waitcnt lgkmcnt(7)
	v_mfma_f32_16x16x32_bf16 v[6:9], v[224:227], v[130:133], v[6:9]
	ds_read_b128 v[224:227], v169 offset:9472
	s_waitcnt lgkmcnt(7)
	v_mfma_f32_16x16x32_bf16 v[10:13], v[228:231], v[62:65], v[6:9]
	ds_read_b128 v[228:231], v169 offset:9984
	s_waitcnt lgkmcnt(7)
	v_mfma_f32_16x16x32_bf16 v[6:9], v[200:203], v[138:141], 0
	v_add_co_u32_e32 v248, vcc, 0x20000, v248
	s_nop 1
	v_addc_co_u32_e32 v249, vcc, 0, v249, vcc
	s_add_i32 m0, s55, 73728
	s_nop 0
	global_load_lds_dwordx4 v[248:249], off
	ds_read_b128 v[200:203], v169 offset:16384
	s_waitcnt lgkmcnt(7)
	v_mfma_f32_16x16x32_bf16 v[6:9], v[204:207], v[134:137], v[6:9]
	ds_read_b128 v[204:207], v169 offset:16896
	s_waitcnt lgkmcnt(7)
	v_mfma_f32_16x16x32_bf16 v[6:9], v[208:211], v[130:133], v[6:9]
	ds_read_b128 v[208:211], v169 offset:17408
	s_waitcnt lgkmcnt(7)
	v_mfma_f32_16x16x32_bf16 v[6:9], v[212:215], v[62:65], v[6:9]
	ds_read_b128 v[212:215], v169 offset:17920
	s_waitcnt lgkmcnt(7)
	v_mfma_f32_16x16x32_bf16 v[14:17], v[216:219], v[138:141], 0
	ds_read_b128 v[216:219], v169 offset:16640
	s_waitcnt lgkmcnt(7)
	v_mfma_f32_16x16x32_bf16 v[14:17], v[220:223], v[134:137], v[14:17]
	ds_read_b128 v[220:223], v169 offset:17152
	s_waitcnt lgkmcnt(7)
	v_mfma_f32_16x16x32_bf16 v[14:17], v[224:227], v[130:133], v[14:17]
	ds_read_b128 v[224:227], v169 offset:17664
	s_waitcnt lgkmcnt(7)
	v_mfma_f32_16x16x32_bf16 v[18:21], v[228:231], v[62:65], v[14:17]
	ds_read_b128 v[228:231], v169 offset:18176
	s_waitcnt lgkmcnt(7)
	v_mfma_f32_16x16x32_bf16 v[14:17], v[200:203], v[138:141], 0
	v_add_co_u32_e32 v248, vcc, 0x20000, v248
	s_nop 1
	v_addc_co_u32_e32 v249, vcc, 0, v249, vcc
	s_add_i32 m0, s55, 81920
	s_nop 0
	global_load_lds_dwordx4 v[248:249], off
	ds_read_b128 v[200:203], v169 offset:24576
	s_waitcnt lgkmcnt(7)
	v_mfma_f32_16x16x32_bf16 v[14:17], v[204:207], v[134:137], v[14:17]
	ds_read_b128 v[204:207], v169 offset:25088
	s_waitcnt lgkmcnt(7)
	v_mfma_f32_16x16x32_bf16 v[14:17], v[208:211], v[130:133], v[14:17]
	ds_read_b128 v[208:211], v169 offset:25600
	s_waitcnt lgkmcnt(7)
	v_mfma_f32_16x16x32_bf16 v[14:17], v[212:215], v[62:65], v[14:17]
	ds_read_b128 v[212:215], v169 offset:26112
	s_waitcnt lgkmcnt(7)
	v_mfma_f32_16x16x32_bf16 v[22:25], v[216:219], v[138:141], 0
	ds_read_b128 v[216:219], v169 offset:24832
	s_waitcnt lgkmcnt(7)
	v_mfma_f32_16x16x32_bf16 v[22:25], v[220:223], v[134:137], v[22:25]
	ds_read_b128 v[220:223], v169 offset:25344
	s_waitcnt lgkmcnt(7)
	v_mfma_f32_16x16x32_bf16 v[22:25], v[224:227], v[130:133], v[22:25]
	ds_read_b128 v[224:227], v169 offset:25856
	s_waitcnt lgkmcnt(7)
	v_mfma_f32_16x16x32_bf16 v[26:29], v[228:231], v[62:65], v[22:25]
	ds_read_b128 v[228:231], v169 offset:26368
	s_waitcnt lgkmcnt(7)
	v_mfma_f32_16x16x32_bf16 v[22:25], v[200:203], v[138:141], 0
	v_add_co_u32_e32 v248, vcc, 0x20000, v248
	s_nop 1
	v_addc_co_u32_e32 v249, vcc, 0, v249, vcc
	s_add_i32 m0, s55, 90112
	s_nop 0
	global_load_lds_dwordx4 v[248:249], off
	ds_read_b128 v[200:203], v169 offset:32768
	s_waitcnt lgkmcnt(7)
	v_mfma_f32_16x16x32_bf16 v[22:25], v[204:207], v[134:137], v[22:25]
	ds_read_b128 v[204:207], v169 offset:33280
	s_waitcnt lgkmcnt(7)
	v_mfma_f32_16x16x32_bf16 v[22:25], v[208:211], v[130:133], v[22:25]
	ds_read_b128 v[208:211], v169 offset:33792
	s_waitcnt lgkmcnt(7)
	v_mfma_f32_16x16x32_bf16 v[22:25], v[212:215], v[62:65], v[22:25]
	ds_read_b128 v[212:215], v169 offset:34304
	s_waitcnt lgkmcnt(7)
	v_mfma_f32_16x16x32_bf16 v[30:33], v[216:219], v[138:141], 0
	ds_read_b128 v[216:219], v169 offset:33024
	s_waitcnt lgkmcnt(7)
	v_mfma_f32_16x16x32_bf16 v[30:33], v[220:223], v[134:137], v[30:33]
	ds_read_b128 v[220:223], v169 offset:33536
	s_waitcnt lgkmcnt(7)
	v_mfma_f32_16x16x32_bf16 v[30:33], v[224:227], v[130:133], v[30:33]
	ds_read_b128 v[224:227], v169 offset:34048
	s_waitcnt lgkmcnt(7)
	v_mfma_f32_16x16x32_bf16 v[34:37], v[228:231], v[62:65], v[30:33]
	ds_read_b128 v[228:231], v169 offset:34560
	s_waitcnt lgkmcnt(7)
	v_mfma_f32_16x16x32_bf16 v[30:33], v[200:203], v[138:141], 0
	v_add_co_u32_e32 v248, vcc, 0x20000, v248
	s_nop 1
	v_addc_co_u32_e32 v249, vcc, 0, v249, vcc
	s_add_i32 m0, s55, 98304
	s_nop 0
	global_load_lds_dwordx4 v[248:249], off
	ds_read_b128 v[200:203], v169 offset:40960
	s_waitcnt lgkmcnt(7)
; #define LAS __attribute__((address_space(3)))
; template <bool LOCAL>
; __device__ __forceinline__ void attn_unit(const bf16_t* Q, const bf16_t* KT, const bf16_t* VT, bf16_t* O, LAS unsigned char* lds, int b, int h, int r, int w, int tq, int lane) {
;     ...
;         const LAS unsigned char* kl = lds + (q >> 2) * 2048 + (((q & 3) * 4 + g) ^ ((q >> 2) & 2)) * 16;
; #pragma unroll
;         for (int p = 0; p < 8; ++p)
; #pragma unroll
;             for (int f = 0; f < 2; ++f) { f32x4 a = {0.f, 0.f, 0.f, 0.f};
; #pragma unroll
;                 for (int ks = 0; ks < 4; ++ks) a = __builtin_amdgcn_mfma_f32_16x16x32_bf16(*(const LAS bf16x8*)(kl + p * 8192 + ks * 512 + f * 256), bq[ks], a, 0, 0, 0);
;                 s[2 * (CP + p) + f] = a; }
; __global__ void __launch_bounds__(NTHREADS, 2) mega(Args args) {
;     ...
;                       for (int ci = tid; ci < 4096; ci += NTHREADS) { const int o = ci >> 7, wq = ci & 127;
;                           const u32x4 kv = *(const u32x4*)(KTp + ((size_t)((oc0 + o) * NH + h)) * 1024 + wq * 8);
;                           *(LAS u32x4*)(lds + o * 2048 + (wq & ~15) * 16 + ((wq & 15) ^ (o & 2)) * 16) = kv;
;                           const u32x4 vv = *(const u32x4*)(VTp + ((size_t)((oc0 + o) * NH + h)) * 1024 + wq * 8);
;                           *(LAS u32x4*)(lds + 65536 + o * 2048 + wq * 16) = vv; }
	v_mfma_f32_16x16x32_bf16 v[30:33], v[204:207], v[134:137], v[30:33]
	ds_read_b128 v[204:207], v169 offset:41472
	s_waitcnt lgkmcnt(7)
	v_mfma_f32_16x16x32_bf16 v[30:33], v[208:211], v[130:133], v[30:33]
	ds_read_b128 v[208:211], v169 offset:41984
	s_waitcnt lgkmcnt(7)
	v_mfma_f32_16x16x32_bf16 v[30:33], v[212:215], v[62:65], v[30:33]
	ds_read_b128 v[212:215], v169 offset:42496
	s_waitcnt lgkmcnt(7)
	v_mfma_f32_16x16x32_bf16 v[38:41], v[216:219], v[138:141], 0
	ds_read_b128 v[216:219], v169 offset:41216
	s_waitcnt lgkmcnt(7)
	v_mfma_f32_16x16x32_bf16 v[38:41], v[220:223], v[134:137], v[38:41]
	ds_read_b128 v[220:223], v169 offset:41728
	s_waitcnt lgkmcnt(7)
	v_mfma_f32_16x16x32_bf16 v[38:41], v[224:227], v[130:133], v[38:41]
	ds_read_b128 v[224:227], v169 offset:42240
	s_waitcnt lgkmcnt(7)
	v_mfma_f32_16x16x32_bf16 v[42:45], v[228:231], v[62:65], v[38:41]
	ds_read_b128 v[228:231], v169 offset:42752
	s_waitcnt lgkmcnt(7)
	v_mfma_f32_16x16x32_bf16 v[38:41], v[200:203], v[138:141], 0
	v_add_co_u32_e32 v248, vcc, 0x20000, v248
	s_nop 1
	v_addc_co_u32_e32 v249, vcc, 0, v249, vcc
	s_add_i32 m0, s55, 106496
	s_nop 0
	global_load_lds_dwordx4 v[248:249], off
	ds_read_b128 v[200:203], v169 offset:49152
	s_waitcnt lgkmcnt(7)
	v_mfma_f32_16x16x32_bf16 v[38:41], v[204:207], v[134:137], v[38:41]
	ds_read_b128 v[204:207], v169 offset:49664
	s_waitcnt lgkmcnt(7)
	v_mfma_f32_16x16x32_bf16 v[38:41], v[208:211], v[130:133], v[38:41]
	ds_read_b128 v[208:211], v169 offset:50176
	s_waitcnt lgkmcnt(7)
	v_mfma_f32_16x16x32_bf16 v[38:41], v[212:215], v[62:65], v[38:41]
	ds_read_b128 v[212:215], v169 offset:50688
	s_waitcnt lgkmcnt(7)
	v_mfma_f32_16x16x32_bf16 v[46:49], v[216:219], v[138:141], 0
	ds_read_b128 v[216:219], v169 offset:49408
	s_waitcnt lgkmcnt(7)
	v_mfma_f32_16x16x32_bf16 v[46:49], v[220:223], v[134:137], v[46:49]
	ds_read_b128 v[220:223], v169 offset:49920
	s_waitcnt lgkmcnt(7)
	v_mfma_f32_16x16x32_bf16 v[46:49], v[224:227], v[130:133], v[46:49]
	ds_read_b128 v[224:227], v169 offset:50432
	s_waitcnt lgkmcnt(7)
	v_mfma_f32_16x16x32_bf16 v[50:53], v[228:231], v[62:65], v[46:49]
	ds_read_b128 v[228:231], v169 offset:50944
	s_waitcnt lgkmcnt(7)
	v_mfma_f32_16x16x32_bf16 v[46:49], v[200:203], v[138:141], 0
	v_add_co_u32_e32 v248, vcc, 0x20000, v248
	s_nop 1
	v_addc_co_u32_e32 v249, vcc, 0, v249, vcc
	s_add_i32 m0, s55, 114688
	s_nop 0
	global_load_lds_dwordx4 v[248:249], off
	ds_read_b128 v[200:203], v169 offset:57344
	s_waitcnt lgkmcnt(7)
	v_mfma_f32_16x16x32_bf16 v[46:49], v[204:207], v[134:137], v[46:49]
	ds_read_b128 v[204:207], v169 offset:57856
	s_waitcnt lgkmcnt(7)
	v_mfma_f32_16x16x32_bf16 v[46:49], v[208:211], v[130:133], v[46:49]
	ds_read_b128 v[208:211], v169 offset:58368
	s_waitcnt lgkmcnt(7)
	v_mfma_f32_16x16x32_bf16 v[46:49], v[212:215], v[62:65], v[46:49]
	ds_read_b128 v[212:215], v169 offset:58880
	s_waitcnt lgkmcnt(7)
	v_mfma_f32_16x16x32_bf16 v[54:57], v[216:219], v[138:141], 0
	ds_read_b128 v[216:219], v169 offset:57600
	s_waitcnt lgkmcnt(7)
	v_mfma_f32_16x16x32_bf16 v[54:57], v[220:223], v[134:137], v[54:57]
	ds_read_b128 v[220:223], v169 offset:58112
	s_waitcnt lgkmcnt(7)
	v_mfma_f32_16x16x32_bf16 v[54:57], v[224:227], v[130:133], v[54:57]
	ds_read_b128 v[224:227], v169 offset:58624
	s_waitcnt lgkmcnt(7)
	v_mfma_f32_16x16x32_bf16 v[58:61], v[228:231], v[62:65], v[54:57]
	ds_read_b128 v[228:231], v169 offset:59136
	s_waitcnt lgkmcnt(7)
	v_mfma_f32_16x16x32_bf16 v[54:57], v[200:203], v[138:141], 0
	v_add_co_u32_e32 v248, vcc, 0x20000, v248
	s_nop 1
	v_addc_co_u32_e32 v249, vcc, 0, v249, vcc
	s_add_i32 m0, s55, 122880
	s_nop 0
	global_load_lds_dwordx4 v[248:249], off
	s_waitcnt lgkmcnt(6)
	v_mfma_f32_16x16x32_bf16 v[54:57], v[204:207], v[134:137], v[54:57]
	s_waitcnt lgkmcnt(5)
	v_mfma_f32_16x16x32_bf16 v[54:57], v[208:211], v[130:133], v[54:57]
	s_waitcnt lgkmcnt(4)
	v_mfma_f32_16x16x32_bf16 v[54:57], v[212:215], v[62:65], v[54:57]
	s_waitcnt lgkmcnt(3)
	v_mfma_f32_16x16x32_bf16 v[138:141], v[216:219], v[138:141], 0
	s_waitcnt lgkmcnt(2)
	v_mfma_f32_16x16x32_bf16 v[134:137], v[220:223], v[134:137], v[138:141]
	s_waitcnt lgkmcnt(1)
	v_mfma_f32_16x16x32_bf16 v[130:133], v[224:227], v[130:133], v[134:137]
	s_waitcnt lgkmcnt(0)
	v_mfma_f32_16x16x32_bf16 v[62:65], v[228:231], v[62:65], v[130:133]
	s_nop 7
	s_nop 2
	s_barrier
; #define LAS __attribute__((address_space(3)))
; template <bool LOCAL>
; __device__ __forceinline__ void attn_unit(const bf16_t* Q, const bf16_t* KT, const bf16_t* VT, bf16_t* O, LAS unsigned char* lds, int b, int h, int r, int w, int tq, int lane) {
;     ...
;     if (LOCAL) { rs = r - 4; rs = rs < 0 ? 0 : (rs > 24 ? 24 : rs); ws = 16 * w - 8; ws = ws < 0 ? 0 : (ws > 32 ? 32 : ws); }
;     const int rgl = b * SEQ + rs * GRID_W + ws;
;     ...
;     if (LOCAL) {
;         const int c = 16 * w + q; int cs = c - 8; cs = cs < 0 ? 0 : (cs > 48 ? 48 : cs);
;         const LAS float* rp = (const LAS float*)(lds + LDS_MISC + 1024);
; #pragma unroll
;         for (int p = 0; p < 8; ++p) { const int ro = (rs + p - r + 7) * 31;
; #pragma unroll
;             for (int f = 0; f < 2; ++f)
; #pragma unroll
;                 for (int j = 0; j < 4; ++j) { const int kc = ws + 8 * g + 4 * f + j; const bool valid = (kc >= cs) && (kc < cs + 16);
;                     int rel = kc - c + 15; rel = rel < 0 ? 0 : (rel > 30 ? 30 : rel);
;                     const float bias = rp[ro + rel];
;                     s[p * 2 + f][j] = valid ? s[p * 2 + f][j] + bias : -INFINITY; } }
;     ...
;         const bf16_t* vloc = VT + ((size_t)(((rgl >> 3) + g) * NH + h)) * 1024 + q * 8;
;         bf16x8 va[2][8];
	s_lshl_b32 s54, s57, 10
	s_add_i32 s59, s54, 0x0
	v_lshlrev_b32_e32 v218, 4, v164
	v_add_u32_e32 v218, s28, v218
	ds_read_b64 v[220:221], v241 offset:192
	s_waitcnt lgkmcnt(0)
	v_add_co_u32_e32 v220, vcc, 0x24300000, v220
	s_nop 1
	v_addc_co_u32_e32 v221, vcc, 0, v221, vcc
	v_add_co_u32_e32 v220, vcc, v220, v218
	s_nop 1
	v_addc_co_u32_e32 v221, vcc, 0, v221, vcc
	v_add_co_u32_e32 v226, vcc, 0x400, v220
	s_nop 1
	v_addc_co_u32_e32 v227, vcc, 0, v221, vcc
	s_and_b32 s55, s57, 3
	s_lshl_b32 s55, s55, 1
	s_add_i32 s55, s55, -1
	s_max_i32 s55, s55, 0
	s_min_i32 s55, s55, 4
	v_add_u32_e32 v219, s55, v165
	v_lshlrev_b32_e32 v224, 4, v166
	v_lshl_add_u32 v219, v219, 10, v224
	s_add_i32 m0, s59, 0
	s_nop 0
	global_load_lds_dwordx4 v[220:221], off
	s_add_i32 m0, s59, 8192
	s_nop 0
	global_load_lds_dwordx4 v[226:227], off
	s_add_i32 m0, s59, 16384
	v_add_co_u32_e32 v222, vcc, s6, v220
	s_nop 1
	v_addc_co_u32_e32 v223, vcc, 0, v221, vcc
	global_load_lds_dwordx4 v[222:223], off
	s_add_i32 m0, s59, 24576
	v_add_co_u32_e32 v222, vcc, s6, v226
	s_nop 1
	v_addc_co_u32_e32 v223, vcc, 0, v227, vcc
	global_load_lds_dwordx4 v[222:223], off
	s_add_i32 m0, s59, 32768
	v_add_co_u32_e32 v222, vcc, s7, v220
	s_nop 1
	v_addc_co_u32_e32 v223, vcc, 0, v221, vcc
	global_load_lds_dwordx4 v[222:223], off
	s_add_i32 m0, s59, 40960
	v_add_co_u32_e32 v222, vcc, s7, v226
	s_nop 1
	v_addc_co_u32_e32 v223, vcc, 0, v227, vcc
	global_load_lds_dwordx4 v[222:223], off
	s_add_i32 m0, s59, 49152
	v_add_co_u32_e32 v222, vcc, s2, v220
	s_nop 1
	v_addc_co_u32_e32 v223, vcc, 0, v221, vcc
	global_load_lds_dwordx4 v[222:223], off
	v_mul_lo_u32 v130, v195, s4
	v_add_u32_e32 v130, 0, v130
	v_add_u32_e32 v135, 0x20400, v130
	v_lshl_add_u32 v130, v170, 2, v135
	v_lshl_add_u32 v131, v171, 2, v135
	v_lshl_add_u32 v201, v172, 2, v135
	v_lshl_add_u32 v203, v173, 2, v135
	v_lshl_add_u32 v204, v174, 2, v135
	v_lshl_add_u32 v205, v175, 2, v135
	v_lshl_add_u32 v206, v176, 2, v135
	v_lshl_add_u32 v207, v177, 2, v135
	v_mov_b32_e32 v246, 0xff800000
	ds_read_b32 v208, v130 offset:928
	ds_read_b32 v209, v131 offset:928
	ds_read_b32 v210, v201 offset:928
	ds_read_b32 v211, v203 offset:928
	ds_read_b32 v212, v204 offset:928
	ds_read_b32 v213, v205 offset:928
	ds_read_b32 v214, v206 offset:928
	ds_read_b32 v215, v207 offset:928
	ds_read_b32 v216, v130 offset:1052
	ds_read_b32 v217, v131 offset:1052
	ds_read_b32 v228, v201 offset:1052
	ds_read_b32 v229, v203 offset:1052
	ds_read_b32 v230, v204 offset:1052
	ds_read_b32 v231, v205 offset:1052
	ds_read_b32 v232, v206 offset:1052
	ds_read_b32 v233, v207 offset:1052
	s_waitcnt lgkmcnt(15)
	v_add_f32_e32 v208, v126, v208
	v_cndmask_b32_e64 v133, v246, v208, s[36:37]
	s_waitcnt lgkmcnt(14)
	v_add_f32_e32 v209, v127, v209
	v_cndmask_b32_e64 v132, v246, v209, s[46:47]
	s_waitcnt lgkmcnt(13)
	v_add_f32_e32 v210, v128, v210
	v_cndmask_b32_e64 v134, v246, v210, s[10:11]
	s_waitcnt lgkmcnt(12)
	v_add_f32_e32 v211, v129, v211
	v_cndmask_b32_e64 v126, v246, v211, s[14:15]
	s_waitcnt lgkmcnt(11)
	v_add_f32_e32 v212, v122, v212
	v_cndmask_b32_e64 v128, v246, v212, s[18:19]
	s_waitcnt lgkmcnt(10)
	v_add_f32_e32 v213, v123, v213
	v_cndmask_b32_e64 v127, v246, v213, s[20:21]
	s_waitcnt lgkmcnt(9)
	v_add_f32_e32 v214, v124, v214
	v_cndmask_b32_e64 v129, v246, v214, s[22:23]
	s_waitcnt lgkmcnt(8)
	v_add_f32_e32 v215, v125, v215
	v_cndmask_b32_e64 v123, v246, v215, s[0:1]
	s_waitcnt lgkmcnt(7)
	v_add_f32_e32 v216, v118, v216
	v_cndmask_b32_e64 v124, v246, v216, s[36:37]
	s_waitcnt lgkmcnt(6)
	v_add_f32_e32 v217, v119, v217
	v_cndmask_b32_e64 v122, v246, v217, s[46:47]
	s_waitcnt lgkmcnt(5)
	v_add_f32_e32 v228, v120, v228
	v_cndmask_b32_e64 v125, v246, v228, s[10:11]
	s_waitcnt lgkmcnt(4)
	v_add_f32_e32 v229, v121, v229
	v_cndmask_b32_e64 v118, v246, v229, s[14:15]
	s_waitcnt lgkmcnt(3)
	v_add_f32_e32 v230, v114, v230
	v_cndmask_b32_e64 v120, v246, v230, s[18:19]
	s_waitcnt lgkmcnt(2)
	v_add_f32_e32 v231, v115, v231
	v_cndmask_b32_e64 v119, v246, v231, s[20:21]
	s_waitcnt lgkmcnt(1)
	v_add_f32_e32 v232, v116, v232
	v_cndmask_b32_e64 v121, v246, v232, s[22:23]
	s_waitcnt lgkmcnt(0)
	v_add_f32_e32 v233, v117, v233
	v_cndmask_b32_e64 v115, v246, v233, s[0:1]
	ds_read_b32 v208, v130 offset:1176
	ds_read_b32 v209, v131 offset:1176
	ds_read_b32 v210, v201 offset:1176
	ds_read_b32 v211, v203 offset:1176
	ds_read_b32 v212, v204 offset:1176
	ds_read_b32 v213, v205 offset:1176
	ds_read_b32 v214, v206 offset:1176
	ds_read_b32 v215, v207 offset:1176
	ds_read_b32 v216, v130 offset:1300
	ds_read_b32 v217, v131 offset:1300
	ds_read_b32 v228, v201 offset:1300
	ds_read_b32 v229, v203 offset:1300
	ds_read_b32 v230, v204 offset:1300
	ds_read_b32 v231, v205 offset:1300
	ds_read_b32 v232, v206 offset:1300
	ds_read_b32 v233, v207 offset:1300
	s_waitcnt lgkmcnt(15)
	v_add_f32_e32 v208, v110, v208
	v_cndmask_b32_e64 v116, v246, v208, s[36:37]
	s_waitcnt lgkmcnt(14)
	v_add_f32_e32 v209, v111, v209
	v_cndmask_b32_e64 v114, v246, v209, s[46:47]
	s_waitcnt lgkmcnt(13)
	v_add_f32_e32 v210, v112, v210
	v_cndmask_b32_e64 v117, v246, v210, s[10:11]
	s_waitcnt lgkmcnt(12)
	v_add_f32_e32 v211, v113, v211
	v_cndmask_b32_e64 v110, v246, v211, s[14:15]
	s_waitcnt lgkmcnt(11)
	v_add_f32_e32 v212, v106, v212
	v_cndmask_b32_e64 v112, v246, v212, s[18:19]
	s_waitcnt lgkmcnt(10)
	v_add_f32_e32 v213, v107, v213
	v_cndmask_b32_e64 v111, v246, v213, s[20:21]
	s_waitcnt lgkmcnt(9)
; #define LAS __attribute__((address_space(3)))
; template <bool LOCAL>
; __device__ __forceinline__ void attn_unit(const bf16_t* Q, const bf16_t* KT, const bf16_t* VT, bf16_t* O, LAS unsigned char* lds, int b, int h, int r, int w, int tq, int lane) {
;     ...
;     if (LOCAL) {
;         const int c = 16 * w + q; int cs = c - 8; cs = cs < 0 ? 0 : (cs > 48 ? 48 : cs);
;         const LAS float* rp = (const LAS float*)(lds + LDS_MISC + 1024);
; #pragma unroll
;         for (int p = 0; p < 8; ++p) { const int ro = (rs + p - r + 7) * 31;
; #pragma unroll
;             for (int f = 0; f < 2; ++f)
; #pragma unroll
;                 for (int j = 0; j < 4; ++j) { const int kc = ws + 8 * g + 4 * f + j; const bool valid = (kc >= cs) && (kc < cs + 16);
;                     int rel = kc - c + 15; rel = rel < 0 ? 0 : (rel > 30 ? 30 : rel);
;                     const float bias = rp[ro + rel];
;                     s[p * 2 + f][j] = valid ? s[p * 2 + f][j] + bias : -INFINITY; } }
	v_add_f32_e32 v214, v108, v214
	v_cndmask_b32_e64 v135, v246, v214, s[22:23]
	s_waitcnt lgkmcnt(8)
	v_add_f32_e32 v215, v109, v215
	v_cndmask_b32_e64 v113, v246, v215, s[0:1]
	s_waitcnt lgkmcnt(7)
	v_add_f32_e32 v216, v102, v216
	v_cndmask_b32_e64 v108, v246, v216, s[36:37]
	s_waitcnt lgkmcnt(6)
	v_add_f32_e32 v217, v103, v217
	v_cndmask_b32_e64 v107, v246, v217, s[46:47]
	s_waitcnt lgkmcnt(5)
	v_add_f32_e32 v228, v104, v228
	v_cndmask_b32_e64 v109, v246, v228, s[10:11]
	s_waitcnt lgkmcnt(4)
	v_add_f32_e32 v229, v105, v229
	v_cndmask_b32_e64 v102, v246, v229, s[14:15]
	s_waitcnt lgkmcnt(3)
	v_add_f32_e32 v230, v98, v230
	v_cndmask_b32_e64 v104, v246, v230, s[18:19]
	s_waitcnt lgkmcnt(2)
	v_add_f32_e32 v231, v99, v231
	v_cndmask_b32_e64 v103, v246, v231, s[20:21]
	s_waitcnt lgkmcnt(1)
	v_add_f32_e32 v232, v100, v232
	v_cndmask_b32_e64 v105, v246, v232, s[22:23]
	s_waitcnt lgkmcnt(0)
	v_add_f32_e32 v233, v101, v233
	v_cndmask_b32_e64 v99, v246, v233, s[0:1]
	ds_read_b32 v208, v130 offset:1424
	ds_read_b32 v209, v131 offset:1424
	ds_read_b32 v210, v201 offset:1424
	ds_read_b32 v211, v203 offset:1424
	ds_read_b32 v212, v204 offset:1424
	ds_read_b32 v213, v205 offset:1424
	ds_read_b32 v214, v206 offset:1424
	ds_read_b32 v215, v207 offset:1424
	ds_read_b32 v216, v130 offset:1548
	ds_read_b32 v217, v131 offset:1548
	ds_read_b32 v228, v201 offset:1548
	ds_read_b32 v229, v203 offset:1548
	ds_read_b32 v230, v204 offset:1548
	ds_read_b32 v231, v205 offset:1548
	ds_read_b32 v232, v206 offset:1548
	ds_read_b32 v233, v207 offset:1548
	s_waitcnt lgkmcnt(15)
	v_add_f32_e32 v208, v94, v208
	v_cndmask_b32_e64 v100, v246, v208, s[36:37]
	s_waitcnt lgkmcnt(14)
	v_add_f32_e32 v209, v95, v209
	v_cndmask_b32_e64 v98, v246, v209, s[46:47]
	s_waitcnt lgkmcnt(13)
	v_add_f32_e32 v210, v96, v210
	v_cndmask_b32_e64 v101, v246, v210, s[10:11]
	s_waitcnt lgkmcnt(12)
	v_add_f32_e32 v211, v97, v211
	v_cndmask_b32_e64 v94, v246, v211, s[14:15]
	s_waitcnt lgkmcnt(11)
	v_add_f32_e32 v212, v90, v212
	v_cndmask_b32_e64 v96, v246, v212, s[18:19]
	s_waitcnt lgkmcnt(10)
	v_add_f32_e32 v213, v91, v213
	v_cndmask_b32_e64 v95, v246, v213, s[20:21]
	s_waitcnt lgkmcnt(9)
	v_add_f32_e32 v214, v92, v214
	v_cndmask_b32_e64 v97, v246, v214, s[22:23]
	s_waitcnt lgkmcnt(8)
	v_add_f32_e32 v215, v93, v215
	v_cndmask_b32_e64 v91, v246, v215, s[0:1]
	s_waitcnt lgkmcnt(7)
	v_add_f32_e32 v216, v86, v216
	v_cndmask_b32_e64 v92, v246, v216, s[36:37]
	s_waitcnt lgkmcnt(6)
	v_add_f32_e32 v217, v87, v217
	v_cndmask_b32_e64 v90, v246, v217, s[46:47]
	s_waitcnt lgkmcnt(5)
	v_add_f32_e32 v228, v88, v228
	v_cndmask_b32_e64 v93, v246, v228, s[10:11]
	s_waitcnt lgkmcnt(4)
	v_add_f32_e32 v229, v89, v229
	v_cndmask_b32_e64 v86, v246, v229, s[14:15]
	s_waitcnt lgkmcnt(3)
	v_add_f32_e32 v230, v82, v230
	v_cndmask_b32_e64 v88, v246, v230, s[18:19]
	s_waitcnt lgkmcnt(2)
	v_add_f32_e32 v231, v83, v231
	v_cndmask_b32_e64 v87, v246, v231, s[20:21]
	s_waitcnt lgkmcnt(1)
	v_add_f32_e32 v232, v84, v232
	v_cndmask_b32_e64 v138, v246, v232, s[22:23]
	s_waitcnt lgkmcnt(0)
	v_add_f32_e32 v233, v85, v233
	v_cndmask_b32_e64 v89, v246, v233, s[0:1]
	ds_read_b32 v208, v130 offset:1672
	ds_read_b32 v209, v131 offset:1672
	ds_read_b32 v210, v201 offset:1672
	ds_read_b32 v211, v203 offset:1672
	ds_read_b32 v212, v204 offset:1672
	ds_read_b32 v213, v205 offset:1672
	ds_read_b32 v214, v206 offset:1672
	ds_read_b32 v215, v207 offset:1672
	ds_read_b32 v216, v130 offset:1796
	ds_read_b32 v217, v131 offset:1796
	ds_read_b32 v228, v201 offset:1796
	ds_read_b32 v229, v203 offset:1796
	ds_read_b32 v230, v204 offset:1796
	ds_read_b32 v231, v205 offset:1796
	ds_read_b32 v232, v206 offset:1796
	ds_read_b32 v233, v207 offset:1796
	s_waitcnt lgkmcnt(15)
	v_add_f32_e32 v208, v78, v208
	v_cndmask_b32_e64 v137, v246, v208, s[36:37]
	s_waitcnt lgkmcnt(14)
	v_add_f32_e32 v209, v79, v209
	v_cndmask_b32_e64 v136, v246, v209, s[46:47]
	s_waitcnt lgkmcnt(13)
	v_add_f32_e32 v210, v80, v210
	v_cndmask_b32_e64 v141, v246, v210, s[10:11]
	s_waitcnt lgkmcnt(12)
	v_add_f32_e32 v211, v81, v211
	v_cndmask_b32_e64 v139, v246, v211, s[14:15]
	s_waitcnt lgkmcnt(11)
	v_add_f32_e32 v212, v74, v212
	v_cndmask_b32_e64 v195, v246, v212, s[18:19]
	s_waitcnt lgkmcnt(10)
	v_add_f32_e32 v213, v75, v213
	v_cndmask_b32_e64 v140, v246, v213, s[20:21]
	s_waitcnt lgkmcnt(9)
	v_add_f32_e32 v214, v76, v214
	v_cndmask_b32_e64 v199, v246, v214, s[22:23]
	s_waitcnt lgkmcnt(8)
	v_add_f32_e32 v215, v77, v215
	v_cndmask_b32_e64 v197, v246, v215, s[0:1]
	s_waitcnt lgkmcnt(7)
	v_add_f32_e32 v216, v70, v216
	v_cndmask_b32_e64 v198, v246, v216, s[36:37]
	s_waitcnt lgkmcnt(6)
	v_add_f32_e32 v217, v71, v217
	v_cndmask_b32_e64 v196, v246, v217, s[46:47]
	s_waitcnt lgkmcnt(5)
	v_add_f32_e32 v228, v72, v228
	v_cndmask_b32_e64 v202, v246, v228, s[10:11]
	s_waitcnt lgkmcnt(4)
	v_add_f32_e32 v229, v73, v229
	v_cndmask_b32_e64 v200, v246, v229, s[14:15]
	s_waitcnt lgkmcnt(3)
	v_add_f32_e32 v230, v66, v230
	v_cndmask_b32_e64 v203, v246, v230, s[18:19]
	s_waitcnt lgkmcnt(2)
	v_add_f32_e32 v231, v67, v231
	v_cndmask_b32_e64 v201, v246, v231, s[20:21]
	s_waitcnt lgkmcnt(1)
	v_add_f32_e32 v232, v68, v232
	v_cndmask_b32_e64 v205, v246, v232, s[22:23]
	s_waitcnt lgkmcnt(0)
	v_add_f32_e32 v233, v69, v233
	v_cndmask_b32_e64 v204, v246, v233, s[0:1]
	s_mov_b64 s[34:35], exec
	s_branch .LBB9_673
